# e3 plus SwiGLU GEMM K-loop restructure: second B half-tile fragment double-buffered in registers so both load segments read 12 fragments (was 16/8); its LDS-DMA restage moved to the SP1 segment
# baseline (speedup 1.0000x reference)
.LBB0_655:
	s_andn2_b64 vcc, exec, s[0:1]
	v_readlane_b32 s3, v255, 30
	s_cbranch_vccnz .LBB0_676
	s_lshl_b32 s8, s3, 7
	v_mbcnt_lo_u32_b32 v0, -1, 0
	v_mbcnt_hi_u32_b32 v0, -1, v0
	s_cmp_ge_i32 s90, s8
	s_waitcnt vmcnt(0)
	v_or_b32_e32 v14, s33, v0
	s_nop 0
	v_readfirstlane_b32 s5, v14
	s_cbranch_scc1 .LBB0_676
	v_lshlrev_b32_e32 v0, 4, v14
	v_add_u32_e32 v2, 0x2000, v0
	v_ashrrev_i32_e32 v3, 31, v2
	v_lshrrev_b32_e32 v3, 22, v3
	v_add_u32_e32 v3, v2, v3
	v_ashrrev_i32_e32 v3, 10, v3
	v_mul_i32_i24_e32 v4, 0x400, v3
	v_sub_u32_e32 v2, v2, v4
	v_lshrrev_b32_e32 v4, 4, v2
	v_bitop3_b32 v2, v4, v2, 32 bitop3:0x6c
	v_ashrrev_i32_e32 v4, 31, v2
	v_lshrrev_b32_e32 v4, 26, v4
	v_add_u32_e32 v4, v2, v4
	v_lshlrev_b32_e32 v6, 3, v3
	v_ashrrev_i32_e32 v5, 6, v4
	v_and_b32_e32 v6, -16, v6
	v_add_u32_e32 v6, v5, v6
	v_and_b32_e32 v5, 3, v5
	s_mov_b32 s0, 0x7fffffe0
	v_lshrrev_b32_e32 v7, 2, v6
	v_lshlrev_b32_e32 v8, 1, v6
	v_lshlrev_b32_e32 v3, 5, v3
	v_and_or_b32 v5, v6, s0, v5
	v_and_b32_e32 v7, 4, v7
	v_and_b32_e32 v8, 24, v8
	v_and_b32_e32 v15, 32, v3
	v_and_b32_e32 v3, 0xc0, v4
	v_or3_b32 v5, v5, v7, v8
	v_sub_u32_e32 v2, v2, v3
	v_mov_b32_e32 v8, 1
	v_ashrrev_i16_sdwa v2, v8, sext(v2) dst_sel:DWORD dst_unused:UNUSED_PAD src0_sel:DWORD src1_sel:BYTE_0
	v_readlane_b32 s12, v255, 27
	v_bfe_i32 v16, v2, 0, 16
	v_add_u32_e32 v2, v15, v16
	v_mul_lo_u32 v5, v5, s12
	v_mul_lo_u32 v17, v6, s12
	v_add_lshl_u32 v130, v5, v2, 1
	v_add_lshl_u32 v132, v2, v17, 1
	v_bfe_i32 v2, v14, 27, 1
	v_lshrrev_b32_e32 v2, 22, v2
	v_add_u32_e32 v2, v0, v2
	v_and_b32_e32 v2, 0xfffffc00, v2
	v_sub_u32_e32 v0, v0, v2
	v_lshrrev_b32_e32 v2, 4, v0
	v_ashrrev_i32_e32 v4, 31, v14
	v_bitop3_b32 v0, v2, v0, 32 bitop3:0x6c
	v_lshrrev_b32_e32 v4, 26, v4
	v_ashrrev_i32_e32 v2, 31, v0
	v_add_u32_e32 v4, v14, v4
	v_lshrrev_b32_e32 v2, 26, v2
	v_ashrrev_i32_e32 v4, 6, v4
	v_add_u32_e32 v2, v0, v2
	v_lshlrev_b32_e32 v5, 3, v4
	v_ashrrev_i32_e32 v3, 6, v2
	v_and_b32_e32 v5, -16, v5
	v_add_u32_e32 v5, v3, v5
	v_and_b32_e32 v3, 3, v3
	s_ashr_i32 s18, s90, 31
	v_and_or_b32 v3, v5, s0, v3
	s_lshr_b32 s0, s18, 29
	s_add_i32 s0, s90, s0
	s_ashr_i32 s6, s5, 6
	s_lshl_b32 s50, s12, 8
	s_lshl_b32 s15, s3, 4
	s_ashr_i32 s1, s0, 3
	s_and_b32 s0, s0, -8
	s_ashr_i32 s7, s5, 8
	s_lshl_b64 s[10:11], s[50:51], 1
	s_lshl_b32 s14, s6, 10
	s_sub_i32 s0, s90, s0
	s_or_b32 s19, s15, 1
	s_cmp_lt_i32 s0, 0
	v_and_b32_e32 v2, 0xc0, v2
	s_cselect_b32 s2, s19, s15
	s_lshl_b32 s24, s3, 3
	v_sub_u32_e32 v0, v0, v2
	v_cvt_f32_u32_e32 v2, s24
	s_sub_i32 s3, 0, s24
	s_mul_i32 s0, s2, s0
	s_add_i32 s0, s0, s1
	v_rcp_iflag_f32_e32 v2, v2
	s_abs_i32 s2, s0
	s_ashr_i32 s1, s0, 31
	v_lshrrev_b32_e32 v6, 2, v5
	v_mul_f32_e32 v2, 0x4f7ffffe, v2
	v_cvt_u32_f32_e32 v2, v2
	v_lshlrev_b32_e32 v7, 1, v5
	v_and_b32_e32 v6, 4, v6
	v_and_b32_e32 v7, 24, v7
	v_readfirstlane_b32 s25, v2
	s_mul_i32 s3, s3, s25
	s_mul_hi_u32 s3, s25, s3
	s_add_i32 s25, s25, s3
	s_mul_hi_u32 s3, s2, s25
	s_mul_i32 s4, s3, s24
	s_sub_i32 s2, s2, s4
	s_add_i32 s4, s3, 1
	s_sub_i32 s9, s2, s24
	s_cmp_ge_u32 s2, s24
	s_cselect_b32 s3, s4, s3
	s_cselect_b32 s2, s9, s2
	s_add_i32 s4, s3, 1
	s_cmp_ge_u32 s2, s24
	s_cselect_b32 s2, s4, s3
	s_xor_b32 s2, s2, s1
	s_sub_i32 s1, s2, s1
	s_lshl_b32 s2, s1, 3
	s_sub_i32 s3, 0x80, s2
	s_min_i32 s3, s3, 8
	s_sext_i32_i16 s4, s3
	v_cvt_f32_i32_e32 v2, s4
	v_lshlrev_b32_e32 v4, 5, v4
	v_ashrrev_i16_sdwa v0, v8, sext(v0) dst_sel:DWORD dst_unused:UNUSED_PAD src0_sel:DWORD src1_sel:BYTE_0
	s_mul_i32 s1, s1, s24
	v_or3_b32 v3, v3, v6, v7
	v_and_b32_e32 v18, 32, v4
	v_bfe_i32 v19, v0, 0, 16
	s_sub_i32 s9, s0, s1
	v_mul_lo_u32 v3, v3, s12
	v_add_u32_e32 v4, v18, v19
	v_mul_lo_u32 v20, v5, s12
	s_sext_i32_i16 s0, s9
	v_add_lshl_u32 v0, v3, v4, 1
	v_add_lshl_u32 v134, v4, v20, 1
	v_cvt_f32_i32_e32 v3, s0
	v_rcp_iflag_f32_e32 v4, v2
	s_xor_b32 s0, s0, s4
	s_ashr_i32 s0, s0, 30
	s_or_b32 s4, s0, 1
	v_mul_f32_e32 v4, v3, v4
	v_trunc_f32_e32 v4, v4
	v_fma_f32 v3, -v4, v2, v3
	v_cvt_i32_f32_e32 v4, v4
	v_cmp_ge_f32_e64 s[0:1], |v3|, |v2|
	s_and_b64 s[0:1], s[0:1], exec
	s_cselect_b32 s0, s4, 0
	v_readfirstlane_b32 s1, v4
	s_add_i32 s4, s1, s0
	s_mul_i32 s0, s4, s3
	s_sub_i32 s0, s9, s0
	s_sext_i32_i16 s0, s0
	s_add_i32 s40, s2, s0
	s_ashr_i32 s0, s40, 31
	s_mul_i32 s0, s10, s0
	s_mul_hi_u32 s1, s10, s40
	s_bfe_u32 s2, s12, 0x10017
	s_add_i32 s0, s1, s0
	s_mul_i32 s1, s2, s40
	s_add_i32 s3, s0, s1
	s_bfe_i64 s[0:1], s[4:5], 0x100000
	s_mul_i32 s1, s10, s1
	s_mul_hi_u32 s12, s10, s0
	s_add_i32 s1, s12, s1
	s_mul_i32 s2, s2, s0
	s_add_i32 s1, s1, s2
	s_mul_i32 s0, s10, s0
	s_add_u32 s0, s16, s0
	s_addc_u32 s1, s17, s1
	s_add_i32 s26, s14, 0
	s_add_i32 m0, s26, 0x10000
	s_mul_i32 s9, s10, s40
	global_load_lds_dwordx4 v0, s[0:1]
	s_add_i32 m0, s26, 0x12000
	s_add_u32 s12, s0, s50
	global_load_lds_dwordx4 v130, s[0:1]
	s_addc_u32 s13, s1, 0
	s_add_i32 m0, s26, 0x14000
	v_readlane_b32 s20, v255, 28
	global_load_lds_dwordx4 v0, s[12:13]
	s_add_i32 m0, s26, 0x16000
	v_readlane_b32 s21, v255, 29
	s_add_u32 s2, s20, s9
	s_addc_u32 s3, s21, s3
	s_add_i32 s27, s26, 0x2000
	global_load_lds_dwordx4 v130, s[12:13]
	s_mov_b32 m0, s26
	s_add_u32 s20, s2, s50
	global_load_lds_dwordx4 v134, s[2:3]
	s_mov_b32 m0, s27
	s_addc_u32 s21, s3, 0
	s_add_i32 s28, s26, 0x4000
	global_load_lds_dwordx4 v132, s[2:3]
	s_mov_b32 m0, s28
	s_add_i32 s29, s26, 0x6000
	global_load_lds_dwordx4 v134, s[20:21]
	s_mov_b32 m0, s29
	v_mov_b32_e32 v131, v1
	global_load_lds_dwordx4 v132, s[20:21]
	v_mov_b32_e32 v135, v1
	v_mov_b32_e32 v133, v1
	s_cmp_eq_u32 s7, 1
	s_waitcnt lgkmcnt(0)
	s_mov_b64 s[78:79], s[22:23]
	s_mov_b64 s[74:75], s[68:69]
	v_lshl_add_u64 v[10:11], s[0:1], 0, v[0:1]
	v_lshl_add_u64 v[6:7], s[0:1], 0, v[130:131]
	v_lshl_add_u64 v[4:5], s[12:13], 0, v[0:1]
	v_lshl_add_u64 v[2:3], s[12:13], 0, v[130:131]
	v_lshl_add_u64 v[8:9], s[2:3], 0, v[134:135]
	s_cselect_b64 s[12:13], -1, 0
	s_cmp_lg_u32 s7, 1
	v_lshl_add_u64 v[12:13], s[2:3], 0, v[132:133]
	v_lshl_add_u64 v[10:11], v[10:11], 0, s[66:67]
	v_lshl_add_u64 v[4:5], v[4:5], 0, s[66:67]
	v_lshl_add_u64 v[2:3], v[2:3], 0, s[66:67]
	s_add_i32 m0, s26, 0x1c000
	s_waitcnt vmcnt(2)
	s_barrier
	global_load_lds_dwordx4 v[4:5], off
	s_add_i32 m0, s26, 0x1e000
	v_lshl_add_u64 v[6:7], v[6:7], 0, s[66:67]
	global_load_lds_dwordx4 v[2:3], off
	s_add_i32 m0, s26, 0x18000
	s_add_i32 s30, s26, 0x8000
	global_load_lds_dwordx4 v[10:11], off
	s_add_i32 m0, s26, 0x1a000
	s_add_i32 s31, s26, 0xa000
	global_load_lds_dwordx4 v[6:7], off
	v_lshl_add_u64 v[6:7], v[8:9], 0, s[66:67]
	s_mov_b32 m0, s30
	s_sext_i32_i16 s41, s4
	global_load_lds_dwordx4 v[6:7], off
	v_lshl_add_u64 v[6:7], v[12:13], 0, s[66:67]
	s_mov_b32 m0, s31
	s_nop 0
	global_load_lds_dwordx4 v[6:7], off
	v_lshrrev_b32_e32 v3, 1, v14
	v_and_b32_e32 v3, 24, v3
	v_and_b32_e32 v2, 15, v14
	v_lshlrev_b32_e32 v4, 1, v3
	v_readlane_b32 s4, v255, 27
	v_lshl_or_b32 v142, s7, 6, v2
	v_lshl_or_b32 v2, v2, 6, v4
	v_lshlrev_b32_e32 v4, 2, v14
	s_lshr_b32 s34, s4, 6
	s_lshl_b32 s4, s7, 13
	v_and_b32_e32 v4, 32, v4
	v_bitop3_b32 v5, v2, s4, v4 bitop3:0xde
	s_lshl_b32 s4, s6, 5
	s_and_b32 s4, s4, 0x60
	s_lshl_b32 s6, s4, 7
	v_bitop3_b32 v143, v2, s6, v4 bitop3:0xde
	v_add_u32_e32 v2, v20, v18
	v_or_b32_e32 v144, s4, v3
	v_add_lshl_u32 v2, v2, v19, 1
	v_mov_b32_e32 v3, v1
	v_add_u32_e32 v222, 0x14000, v143
	ds_read_b128 v[162:165], v222
	ds_read_b128 v[166:169], v222 offset:1024
	ds_read_b128 v[170:173], v222 offset:2048
	ds_read_b128 v[174:177], v222 offset:3072
	s_waitcnt lgkmcnt(0)
	s_cmp_lg_u32 s7, 1
	s_cbranch_scc1 .Lmy_sw_skip
	s_barrier
.Lmy_sw_skip:
	s_waitcnt vmcnt(6)
	s_add_i32 s35, s34, -2
	v_lshl_add_u64 v[136:137], s[50:51], 0, v[2:3]
	v_add_u32_e32 v2, v17, v15
	s_cmpk_lt_u32 s5, 0x100
	v_add_lshl_u32 v2, v2, v16, 1
	s_cselect_b64 s[20:21], -1, 0
	s_ashr_i32 s36, s42, 31
	s_mov_b32 s9, s51
	v_lshl_add_u64 v[138:139], s[50:51], 0, v[2:3]
	s_mov_b32 s37, 0
	v_add_u32_e32 v145, 0, v5
	s_barrier
	s_branch .LBB0_662

.LBB0_669:
	s_add_i32 s53, s0, 2
	s_add_u32 s55, s2, 0x80
	s_addc_u32 s1, s3, 0
	s_add_i32 s68, 0, 0x10000
	s_cmp_eq_u32 s35, s0
	s_cselect_b32 s1, s7, s1
	s_cselect_b32 s0, s6, s55
	v_add_u32_e32 v140, s68, v143
	s_cselect_b32 s65, s23, s52
	s_cselect_b32 s64, s22, s43
	s_add_i32 s55, 0, 0x14000
	ds_read_b128 v[146:149], v140
	ds_read_b128 v[150:153], v140 offset:1024
	ds_read_b128 v[154:157], v140 offset:2048
	ds_read_b128 v[158:161], v140 offset:3072
	v_lshl_add_u64 v[140:141], s[2:3], 0, v[136:137]
	s_add_i32 m0, s26, 0xc000
	ds_read_b128 v[178:181], v145
	ds_read_b128 v[182:185], v145 offset:1024
	ds_read_b128 v[186:189], v145 offset:2048
	ds_read_b128 v[190:193], v145 offset:3072
	ds_read_b128 v[194:197], v145 offset:4096
	ds_read_b128 v[198:201], v145 offset:5120
	ds_read_b128 v[202:205], v145 offset:6144
	ds_read_b128 v[206:209], v145 offset:7168
	global_load_lds_dwordx4 v[140:141], off
	v_lshl_add_u64 v[140:141], s[2:3], 0, v[138:139]
	s_add_i32 m0, s26, 0xe000
	v_lshl_add_u64 v[212:213], s[64:65], 0, v[0:1]
	global_load_lds_dwordx4 v[140:141], off
	v_lshl_add_u64 v[214:215], s[64:65], 0, v[130:131]
	v_lshl_add_u64 v[212:213], v[212:213], 0, s[50:51]
	s_add_i32 m0, s26, 0x14000
	v_lshl_add_u64 v[214:215], v[214:215], 0, s[50:51]
	global_load_lds_dwordx4 v[212:213], off
	s_add_i32 m0, s26, 0x16000
	s_nop 0
	global_load_lds_dwordx4 v[214:215], off
	s_waitcnt vmcnt(8)
	s_waitcnt lgkmcnt(0)
	s_barrier
	s_setprio 1
	s_waitcnt lgkmcnt(0)
	v_mfma_f32_16x16x32_bf16 v[126:129], v[146:149], v[178:181], v[126:129]
	v_mfma_f32_16x16x32_bf16 v[118:121], v[154:157], v[178:181], v[118:121]
	v_mfma_f32_16x16x32_bf16 v[110:113], v[146:149], v[186:189], v[110:113]
	v_mfma_f32_16x16x32_bf16 v[102:105], v[154:157], v[186:189], v[102:105]
	v_mfma_f32_16x16x32_bf16 v[94:97], v[146:149], v[194:197], v[94:97]
	v_mfma_f32_16x16x32_bf16 v[86:89], v[154:157], v[194:197], v[86:89]
	v_mfma_f32_16x16x32_bf16 v[78:81], v[146:149], v[202:205], v[78:81]
	v_mfma_f32_16x16x32_bf16 v[70:73], v[154:157], v[202:205], v[70:73]
	v_mfma_f32_16x16x32_bf16 v[126:129], v[150:153], v[182:185], v[126:129]
	v_mfma_f32_16x16x32_bf16 v[118:121], v[158:161], v[182:185], v[118:121]
	v_mfma_f32_16x16x32_bf16 v[110:113], v[150:153], v[190:193], v[110:113]
	v_mfma_f32_16x16x32_bf16 v[102:105], v[158:161], v[190:193], v[102:105]
	v_mfma_f32_16x16x32_bf16 v[94:97], v[150:153], v[198:201], v[94:97]
	v_mfma_f32_16x16x32_bf16 v[86:89], v[158:161], v[198:201], v[86:89]
	v_mfma_f32_16x16x32_bf16 v[78:81], v[150:153], v[206:209], v[78:81]
	v_mfma_f32_16x16x32_bf16 v[70:73], v[158:161], v[206:209], v[70:73]
	s_setprio 0
	s_setprio 1
	v_mfma_f32_16x16x32_bf16 v[122:125], v[162:165], v[178:181], v[122:125]
	v_mfma_f32_16x16x32_bf16 v[114:117], v[170:173], v[178:181], v[114:117]
	v_mfma_f32_16x16x32_bf16 v[106:109], v[162:165], v[186:189], v[106:109]
	v_mfma_f32_16x16x32_bf16 v[98:101], v[170:173], v[186:189], v[98:101]
	v_mfma_f32_16x16x32_bf16 v[90:93], v[162:165], v[194:197], v[90:93]
	v_mfma_f32_16x16x32_bf16 v[82:85], v[170:173], v[194:197], v[82:85]
	v_mfma_f32_16x16x32_bf16 v[74:77], v[162:165], v[202:205], v[74:77]
	v_mfma_f32_16x16x32_bf16 v[66:69], v[170:173], v[202:205], v[66:69]
	v_mfma_f32_16x16x32_bf16 v[122:125], v[166:169], v[182:185], v[122:125]
	v_mfma_f32_16x16x32_bf16 v[114:117], v[174:177], v[182:185], v[114:117]
	v_mfma_f32_16x16x32_bf16 v[106:109], v[166:169], v[190:193], v[106:109]
	v_mfma_f32_16x16x32_bf16 v[98:101], v[174:177], v[190:193], v[98:101]
	v_mfma_f32_16x16x32_bf16 v[90:93], v[166:169], v[198:201], v[90:93]
	v_mfma_f32_16x16x32_bf16 v[82:85], v[174:177], v[198:201], v[82:85]
	v_mfma_f32_16x16x32_bf16 v[74:77], v[166:169], v[206:209], v[74:77]
	v_mfma_f32_16x16x32_bf16 v[66:69], v[174:177], v[206:209], v[66:69]
	s_setprio 0
	s_barrier
	s_add_i32 s68, s68, s14
	v_lshl_add_u64 v[140:141], s[64:65], 0, v[0:1]
	s_mov_b32 m0, s68
	ds_read_b128 v[178:181], v145 offset:16384
	ds_read_b128 v[182:185], v145 offset:17408
	ds_read_b128 v[186:189], v145 offset:18432
	ds_read_b128 v[190:193], v145 offset:19456
	ds_read_b128 v[194:197], v145 offset:20480
	ds_read_b128 v[198:201], v145 offset:21504
	ds_read_b128 v[202:205], v145 offset:22528
	ds_read_b128 v[206:209], v145 offset:23552
	v_add_u32_e32 v222, 0x1c000, v143
	global_load_lds_dwordx4 v[140:141], off
	ds_read_b128 v[224:227], v222
	ds_read_b128 v[228:231], v222 offset:1024
	ds_read_b128 v[232:235], v222 offset:2048
	ds_read_b128 v[236:239], v222 offset:3072
	s_add_i32 m0, s68, 0x2000
	v_lshl_add_u64 v[210:211], s[64:65], 0, v[130:131]
	v_lshl_add_u64 v[216:217], s[0:1], 0, v[134:135]
	global_load_lds_dwordx4 v[210:211], off
	s_mov_b32 m0, s26
	v_lshl_add_u64 v[218:219], s[0:1], 0, v[132:133]
	global_load_lds_dwordx4 v[216:217], off
	s_mov_b32 m0, s27
	s_nop 0
	global_load_lds_dwordx4 v[218:219], off
	s_waitcnt vmcnt(8)
	s_waitcnt lgkmcnt(0)
	s_barrier
	s_setprio 1
	s_waitcnt lgkmcnt(0)
	v_mfma_f32_16x16x32_bf16 v[62:65], v[146:149], v[178:181], v[62:65]
	v_mfma_f32_16x16x32_bf16 v[54:57], v[154:157], v[178:181], v[54:57]
	v_mfma_f32_16x16x32_bf16 v[46:49], v[146:149], v[186:189], v[46:49]
	v_mfma_f32_16x16x32_bf16 v[38:41], v[154:157], v[186:189], v[38:41]
	v_mfma_f32_16x16x32_bf16 v[30:33], v[146:149], v[194:197], v[30:33]
	v_mfma_f32_16x16x32_bf16 v[22:25], v[154:157], v[194:197], v[22:25]
	v_mfma_f32_16x16x32_bf16 v[14:17], v[146:149], v[202:205], v[14:17]
	v_mfma_f32_16x16x32_bf16 v[6:9], v[154:157], v[202:205], v[6:9]
	v_mfma_f32_16x16x32_bf16 v[62:65], v[150:153], v[182:185], v[62:65]
	v_mfma_f32_16x16x32_bf16 v[54:57], v[158:161], v[182:185], v[54:57]
	v_mfma_f32_16x16x32_bf16 v[46:49], v[150:153], v[190:193], v[46:49]
	v_mfma_f32_16x16x32_bf16 v[38:41], v[158:161], v[190:193], v[38:41]
	v_mfma_f32_16x16x32_bf16 v[30:33], v[150:153], v[198:201], v[30:33]
	v_mfma_f32_16x16x32_bf16 v[22:25], v[158:161], v[198:201], v[22:25]
	v_mfma_f32_16x16x32_bf16 v[14:17], v[150:153], v[206:209], v[14:17]
	v_mfma_f32_16x16x32_bf16 v[6:9], v[158:161], v[206:209], v[6:9]
	s_setprio 0
	s_setprio 1
	v_mfma_f32_16x16x32_bf16 v[58:61], v[162:165], v[178:181], v[58:61]
	v_mfma_f32_16x16x32_bf16 v[50:53], v[170:173], v[178:181], v[50:53]
	v_mfma_f32_16x16x32_bf16 v[42:45], v[162:165], v[186:189], v[42:45]
	v_mfma_f32_16x16x32_bf16 v[34:37], v[170:173], v[186:189], v[34:37]
	v_mfma_f32_16x16x32_bf16 v[26:29], v[162:165], v[194:197], v[26:29]
	v_mfma_f32_16x16x32_bf16 v[18:21], v[170:173], v[194:197], v[18:21]
	v_mfma_f32_16x16x32_bf16 v[10:13], v[162:165], v[202:205], v[10:13]
	v_mfma_f32_16x16x32_bf16 v[2:5], v[170:173], v[202:205], v[2:5]
	v_mfma_f32_16x16x32_bf16 v[58:61], v[166:169], v[182:185], v[58:61]
	v_mfma_f32_16x16x32_bf16 v[50:53], v[174:177], v[182:185], v[50:53]
	v_mfma_f32_16x16x32_bf16 v[42:45], v[166:169], v[190:193], v[42:45]
	v_mfma_f32_16x16x32_bf16 v[34:37], v[174:177], v[190:193], v[34:37]
	v_mfma_f32_16x16x32_bf16 v[26:29], v[166:169], v[198:201], v[26:29]
	v_mfma_f32_16x16x32_bf16 v[18:21], v[174:177], v[198:201], v[18:21]
	v_mfma_f32_16x16x32_bf16 v[10:13], v[166:169], v[206:209], v[10:13]
	v_mfma_f32_16x16x32_bf16 v[2:5], v[174:177], v[206:209], v[2:5]
	s_setprio 0
	s_barrier
	s_add_i32 s55, 0, 0x18000
	s_add_i32 s64, 0, 0x1c000
	v_add_u32_e32 v158, s55, v143
	ds_read_b128 v[146:149], v158
	ds_read_b128 v[150:153], v158 offset:1024
	ds_read_b128 v[154:157], v158 offset:2048
	ds_read_b128 v[158:161], v158 offset:3072
	s_add_u32 s0, s0, s50
	s_addc_u32 s1, s1, 0
	s_mov_b32 m0, s28
	v_lshl_add_u64 v[220:221], s[0:1], 0, v[134:135]
	ds_read_b128 v[178:181], v145 offset:32768
	ds_read_b128 v[182:185], v145 offset:33792
	ds_read_b128 v[186:189], v145 offset:34816
	ds_read_b128 v[190:193], v145 offset:35840
	ds_read_b128 v[194:197], v145 offset:36864
	ds_read_b128 v[198:201], v145 offset:37888
	ds_read_b128 v[202:205], v145 offset:38912
	ds_read_b128 v[206:209], v145 offset:39936
	global_load_lds_dwordx4 v[220:221], off
	v_lshl_add_u64 v[220:221], s[0:1], 0, v[132:133]
	s_mov_b32 m0, s29
	v_lshl_add_u64 v[212:213], v[212:213], 0, s[66:67]
	global_load_lds_dwordx4 v[220:221], off
	v_lshl_add_u64 v[214:215], v[214:215], 0, s[66:67]
	s_add_i32 m0, s26, 0x1c000
	s_nop 0
	global_load_lds_dwordx4 v[212:213], off
	s_add_i32 m0, s26, 0x1e000
	s_nop 0
	global_load_lds_dwordx4 v[214:215], off
	s_waitcnt vmcnt(8)
	s_waitcnt lgkmcnt(0)
	s_barrier
	s_setprio 1
	s_waitcnt lgkmcnt(0)
	v_mfma_f32_16x16x32_bf16 v[126:129], v[146:149], v[178:181], v[126:129]
	v_mfma_f32_16x16x32_bf16 v[118:121], v[154:157], v[178:181], v[118:121]
	v_mfma_f32_16x16x32_bf16 v[110:113], v[146:149], v[186:189], v[110:113]
	v_mfma_f32_16x16x32_bf16 v[102:105], v[154:157], v[186:189], v[102:105]
	v_mfma_f32_16x16x32_bf16 v[94:97], v[146:149], v[194:197], v[94:97]
	v_mfma_f32_16x16x32_bf16 v[86:89], v[154:157], v[194:197], v[86:89]
	v_mfma_f32_16x16x32_bf16 v[78:81], v[146:149], v[202:205], v[78:81]
	v_mfma_f32_16x16x32_bf16 v[70:73], v[154:157], v[202:205], v[70:73]
	v_mfma_f32_16x16x32_bf16 v[126:129], v[150:153], v[182:185], v[126:129]
	v_mfma_f32_16x16x32_bf16 v[118:121], v[158:161], v[182:185], v[118:121]
	v_mfma_f32_16x16x32_bf16 v[110:113], v[150:153], v[190:193], v[110:113]
	v_mfma_f32_16x16x32_bf16 v[102:105], v[158:161], v[190:193], v[102:105]
	v_mfma_f32_16x16x32_bf16 v[94:97], v[150:153], v[198:201], v[94:97]
	v_mfma_f32_16x16x32_bf16 v[86:89], v[158:161], v[198:201], v[86:89]
	v_mfma_f32_16x16x32_bf16 v[78:81], v[150:153], v[206:209], v[78:81]
	v_mfma_f32_16x16x32_bf16 v[70:73], v[158:161], v[206:209], v[70:73]
	s_setprio 0
	s_setprio 1
	v_mfma_f32_16x16x32_bf16 v[122:125], v[224:227], v[178:181], v[122:125]
	v_mfma_f32_16x16x32_bf16 v[114:117], v[232:235], v[178:181], v[114:117]
	v_mfma_f32_16x16x32_bf16 v[106:109], v[224:227], v[186:189], v[106:109]
	v_mfma_f32_16x16x32_bf16 v[98:101], v[232:235], v[186:189], v[98:101]
	v_mfma_f32_16x16x32_bf16 v[90:93], v[224:227], v[194:197], v[90:93]
	v_mfma_f32_16x16x32_bf16 v[82:85], v[232:235], v[194:197], v[82:85]
	v_mfma_f32_16x16x32_bf16 v[74:77], v[224:227], v[202:205], v[74:77]
	v_mfma_f32_16x16x32_bf16 v[66:69], v[232:235], v[202:205], v[66:69]
	v_mfma_f32_16x16x32_bf16 v[122:125], v[228:231], v[182:185], v[122:125]
	v_mfma_f32_16x16x32_bf16 v[114:117], v[236:239], v[182:185], v[114:117]
	v_mfma_f32_16x16x32_bf16 v[106:109], v[228:231], v[190:193], v[106:109]
	v_mfma_f32_16x16x32_bf16 v[98:101], v[236:239], v[190:193], v[98:101]
	v_mfma_f32_16x16x32_bf16 v[90:93], v[228:231], v[198:201], v[90:93]
	v_mfma_f32_16x16x32_bf16 v[82:85], v[236:239], v[198:201], v[82:85]
	v_mfma_f32_16x16x32_bf16 v[74:77], v[228:231], v[206:209], v[74:77]
	v_mfma_f32_16x16x32_bf16 v[66:69], v[236:239], v[206:209], v[66:69]
	s_setprio 0
	s_barrier
	s_add_i32 s0, s55, s14
	v_lshl_add_u64 v[140:141], v[140:141], 0, s[66:67]
	s_mov_b32 m0, s0
	ds_read_b128 v[178:181], v145 offset:49152
	ds_read_b128 v[182:185], v145 offset:50176
	ds_read_b128 v[186:189], v145 offset:51200
	ds_read_b128 v[190:193], v145 offset:52224
	ds_read_b128 v[194:197], v145 offset:53248
	ds_read_b128 v[198:201], v145 offset:54272
	ds_read_b128 v[202:205], v145 offset:55296
	ds_read_b128 v[206:209], v145 offset:56320
	v_add_u32_e32 v222, 0x14000, v143
	global_load_lds_dwordx4 v[140:141], off
	ds_read_b128 v[162:165], v222
	ds_read_b128 v[166:169], v222 offset:1024
	ds_read_b128 v[170:173], v222 offset:2048
	ds_read_b128 v[174:177], v222 offset:3072
	v_lshl_add_u64 v[140:141], v[210:211], 0, s[66:67]
	s_add_i32 m0, s0, 0x2000
	s_nop 0
	global_load_lds_dwordx4 v[140:141], off
	v_lshl_add_u64 v[140:141], v[216:217], 0, s[66:67]
	s_mov_b32 m0, s30
	s_nop 0
	global_load_lds_dwordx4 v[140:141], off
	v_lshl_add_u64 v[140:141], v[218:219], 0, s[66:67]
	s_mov_b32 m0, s31
	s_nop 0
	global_load_lds_dwordx4 v[140:141], off
	s_waitcnt vmcnt(8)
	s_waitcnt lgkmcnt(0)
	s_barrier
	s_setprio 1
	s_waitcnt lgkmcnt(0)
	v_mfma_f32_16x16x32_bf16 v[62:65], v[146:149], v[178:181], v[62:65]
	v_mfma_f32_16x16x32_bf16 v[54:57], v[154:157], v[178:181], v[54:57]
	v_mfma_f32_16x16x32_bf16 v[46:49], v[146:149], v[186:189], v[46:49]
	v_mfma_f32_16x16x32_bf16 v[38:41], v[154:157], v[186:189], v[38:41]
	v_mfma_f32_16x16x32_bf16 v[30:33], v[146:149], v[194:197], v[30:33]
	v_mfma_f32_16x16x32_bf16 v[22:25], v[154:157], v[194:197], v[22:25]
	v_mfma_f32_16x16x32_bf16 v[14:17], v[146:149], v[202:205], v[14:17]
	v_mfma_f32_16x16x32_bf16 v[6:9], v[154:157], v[202:205], v[6:9]
	v_mfma_f32_16x16x32_bf16 v[62:65], v[150:153], v[182:185], v[62:65]
	v_mfma_f32_16x16x32_bf16 v[54:57], v[158:161], v[182:185], v[54:57]
	v_mfma_f32_16x16x32_bf16 v[46:49], v[150:153], v[190:193], v[46:49]
	v_mfma_f32_16x16x32_bf16 v[38:41], v[158:161], v[190:193], v[38:41]
	v_mfma_f32_16x16x32_bf16 v[30:33], v[150:153], v[198:201], v[30:33]
	v_mfma_f32_16x16x32_bf16 v[22:25], v[158:161], v[198:201], v[22:25]
	v_mfma_f32_16x16x32_bf16 v[14:17], v[150:153], v[206:209], v[14:17]
	v_mfma_f32_16x16x32_bf16 v[6:9], v[158:161], v[206:209], v[6:9]
	s_setprio 0
	s_setprio 1
	v_mfma_f32_16x16x32_bf16 v[58:61], v[224:227], v[178:181], v[58:61]
	v_mfma_f32_16x16x32_bf16 v[50:53], v[232:235], v[178:181], v[50:53]
	v_mfma_f32_16x16x32_bf16 v[42:45], v[224:227], v[186:189], v[42:45]
	v_mfma_f32_16x16x32_bf16 v[34:37], v[232:235], v[186:189], v[34:37]
	v_mfma_f32_16x16x32_bf16 v[26:29], v[224:227], v[194:197], v[26:29]
	v_mfma_f32_16x16x32_bf16 v[18:21], v[232:235], v[194:197], v[18:21]
	v_mfma_f32_16x16x32_bf16 v[10:13], v[224:227], v[202:205], v[10:13]
	v_mfma_f32_16x16x32_bf16 v[2:5], v[232:235], v[202:205], v[2:5]
	v_mfma_f32_16x16x32_bf16 v[58:61], v[228:231], v[182:185], v[58:61]
	v_mfma_f32_16x16x32_bf16 v[50:53], v[236:239], v[182:185], v[50:53]
	v_mfma_f32_16x16x32_bf16 v[42:45], v[228:231], v[190:193], v[42:45]
	v_mfma_f32_16x16x32_bf16 v[34:37], v[236:239], v[190:193], v[34:37]
	v_mfma_f32_16x16x32_bf16 v[26:29], v[228:231], v[198:201], v[26:29]
	v_mfma_f32_16x16x32_bf16 v[18:21], v[236:239], v[198:201], v[18:21]
	v_mfma_f32_16x16x32_bf16 v[10:13], v[228:231], v[206:209], v[10:13]
	v_mfma_f32_16x16x32_bf16 v[2:5], v[236:239], v[206:209], v[2:5]
	s_setprio 0
	s_barrier
	s_add_u32 s2, s2, 0x100
	s_addc_u32 s3, s3, 0
	s_add_u32 s43, s43, 0x100
	s_addc_u32 s52, s52, 0
	s_cmp_ge_u32 s53, s34
	s_mov_b32 s0, s53
	s_cbranch_scc0 .LBB0_669
	s_and_b64 vcc, exec, s[20:21]
	s_cbranch_vccz .LBB0_672
	s_barrier
.LBB0_672:
	v_readlane_b32 s0, v255, 17
	v_lshl_or_b32 v148, s41, 7, v144
	v_readlane_b32 s1, v255, 18
	v_lshl_add_u32 v146, s40, 8, v142
	s_movk_i32 s2, 0x1600
	v_lshlrev_b32_e32 v149, 1, v148
	v_mov_b32_e32 v150, 0xbfb8aa3b
	v_mov_b32_e32 v151, 0xbfb8aa3b
	v_mov_b32_e32 v152, 1.0
	v_mov_b32_e32 v153, 1.0
	v_mad_u32_u24 v140, v146, s2, v149
	v_pk_mul_f32 v[178:179], v[126:127], v[150:151]
	v_pk_mul_f32 v[180:181], v[128:129], v[150:151]
	v_pk_mul_f32 v[182:183], v[118:119], v[150:151]
	v_pk_mul_f32 v[184:185], v[120:121], v[150:151]
	v_pk_mul_f32 v[186:187], v[110:111], v[150:151]
	v_pk_mul_f32 v[188:189], v[112:113], v[150:151]
	v_pk_mul_f32 v[190:191], v[102:103], v[150:151]
	v_pk_mul_f32 v[192:193], v[104:105], v[150:151]
	v_exp_f32_e32 v178, v178
	v_exp_f32_e32 v179, v179
	v_exp_f32_e32 v180, v180
	v_exp_f32_e32 v181, v181
	v_exp_f32_e32 v182, v182
	v_exp_f32_e32 v183, v183
	v_exp_f32_e32 v184, v184
	v_exp_f32_e32 v185, v185
	v_exp_f32_e32 v186, v186
	v_exp_f32_e32 v187, v187
	v_exp_f32_e32 v188, v188
	v_exp_f32_e32 v189, v189
	v_exp_f32_e32 v190, v190
	v_exp_f32_e32 v191, v191
	v_exp_f32_e32 v192, v192
	v_exp_f32_e32 v193, v193
	v_pk_add_f32 v[178:179], v[178:179], v[152:153]
	v_pk_add_f32 v[180:181], v[180:181], v[152:153]
	v_pk_add_f32 v[182:183], v[182:183], v[152:153]
	v_pk_add_f32 v[184:185], v[184:185], v[152:153]
	v_pk_add_f32 v[186:187], v[186:187], v[152:153]
	v_pk_add_f32 v[188:189], v[188:189], v[152:153]
	v_pk_add_f32 v[190:191], v[190:191], v[152:153]
	v_pk_add_f32 v[192:193], v[192:193], v[152:153]
	v_rcp_f32_e32 v178, v178
	v_rcp_f32_e32 v179, v179
	v_rcp_f32_e32 v180, v180
	v_rcp_f32_e32 v181, v181
	v_rcp_f32_e32 v182, v182
	v_rcp_f32_e32 v183, v183
	v_rcp_f32_e32 v184, v184
	v_rcp_f32_e32 v185, v185
	v_rcp_f32_e32 v186, v186
	v_rcp_f32_e32 v187, v187
	v_rcp_f32_e32 v188, v188
	v_rcp_f32_e32 v189, v189
	v_rcp_f32_e32 v190, v190
	v_rcp_f32_e32 v191, v191
	v_rcp_f32_e32 v192, v192
	v_rcp_f32_e32 v193, v193
	v_pk_mul_f32 v[178:179], v[126:127], v[178:179]
	v_pk_mul_f32 v[180:181], v[128:129], v[180:181]
	v_pk_mul_f32 v[182:183], v[118:119], v[182:183]
	v_pk_mul_f32 v[184:185], v[120:121], v[184:185]
	v_pk_mul_f32 v[186:187], v[110:111], v[186:187]
	v_pk_mul_f32 v[188:189], v[112:113], v[188:189]
	v_pk_mul_f32 v[190:191], v[102:103], v[190:191]
	v_pk_mul_f32 v[192:193], v[104:105], v[192:193]
	v_pk_mul_f32 v[178:179], v[178:179], v[122:123]
	v_pk_mul_f32 v[180:181], v[180:181], v[124:125]
	v_pk_mul_f32 v[182:183], v[182:183], v[114:115]
	v_pk_mul_f32 v[184:185], v[184:185], v[116:117]
	v_pk_mul_f32 v[186:187], v[186:187], v[106:107]
	v_pk_mul_f32 v[188:189], v[188:189], v[108:109]
	v_pk_mul_f32 v[190:191], v[190:191], v[98:99]
	v_pk_mul_f32 v[192:193], v[192:193], v[100:101]
	v_cvt_pk_bf16_f32 v178, v178, v179
	v_cvt_pk_bf16_f32 v179, v180, v181
	v_cvt_pk_bf16_f32 v180, v182, v183
	v_cvt_pk_bf16_f32 v181, v184, v185
	v_cvt_pk_bf16_f32 v186, v186, v187
	v_cvt_pk_bf16_f32 v187, v188, v189
	v_cvt_pk_bf16_f32 v188, v190, v191
	v_cvt_pk_bf16_f32 v189, v192, v193
	global_store_dwordx4 v140, v[178:181], s[0:1]
	v_add_u32_e32 v147, 0x16000, v140
	global_store_dwordx4 v147, v[186:189], s[0:1]
	v_pk_mul_f32 v[194:195], v[94:95], v[150:151]
	v_pk_mul_f32 v[196:197], v[96:97], v[150:151]
	v_pk_mul_f32 v[198:199], v[86:87], v[150:151]
	v_pk_mul_f32 v[200:201], v[88:89], v[150:151]
	v_pk_mul_f32 v[202:203], v[78:79], v[150:151]
	v_pk_mul_f32 v[204:205], v[80:81], v[150:151]
	v_pk_mul_f32 v[206:207], v[70:71], v[150:151]
	v_pk_mul_f32 v[208:209], v[72:73], v[150:151]
	v_exp_f32_e32 v194, v194
	v_exp_f32_e32 v195, v195
	v_exp_f32_e32 v196, v196
	v_exp_f32_e32 v197, v197
	v_exp_f32_e32 v198, v198
	v_exp_f32_e32 v199, v199
	v_exp_f32_e32 v200, v200
	v_exp_f32_e32 v201, v201
	v_exp_f32_e32 v202, v202
	v_exp_f32_e32 v203, v203
	v_exp_f32_e32 v204, v204
	v_exp_f32_e32 v205, v205
	v_exp_f32_e32 v206, v206
	v_exp_f32_e32 v207, v207
	v_exp_f32_e32 v208, v208
	v_exp_f32_e32 v209, v209
	v_pk_add_f32 v[194:195], v[194:195], v[152:153]
	v_pk_add_f32 v[196:197], v[196:197], v[152:153]
	v_pk_add_f32 v[198:199], v[198:199], v[152:153]
	v_pk_add_f32 v[200:201], v[200:201], v[152:153]
	v_pk_add_f32 v[202:203], v[202:203], v[152:153]
	v_pk_add_f32 v[204:205], v[204:205], v[152:153]
	v_pk_add_f32 v[206:207], v[206:207], v[152:153]
	v_pk_add_f32 v[208:209], v[208:209], v[152:153]
	v_rcp_f32_e32 v194, v194
	v_rcp_f32_e32 v195, v195
	v_rcp_f32_e32 v196, v196
	v_rcp_f32_e32 v197, v197
	v_rcp_f32_e32 v198, v198
	v_rcp_f32_e32 v199, v199
	v_rcp_f32_e32 v200, v200
	v_rcp_f32_e32 v201, v201
	v_rcp_f32_e32 v202, v202
	v_rcp_f32_e32 v203, v203
	v_rcp_f32_e32 v204, v204
	v_rcp_f32_e32 v205, v205
	v_rcp_f32_e32 v206, v206
	v_rcp_f32_e32 v207, v207
	v_rcp_f32_e32 v208, v208
	v_rcp_f32_e32 v209, v209
	v_pk_mul_f32 v[194:195], v[94:95], v[194:195]
	v_pk_mul_f32 v[196:197], v[96:97], v[196:197]
	v_pk_mul_f32 v[198:199], v[86:87], v[198:199]
	v_pk_mul_f32 v[200:201], v[88:89], v[200:201]
	v_pk_mul_f32 v[202:203], v[78:79], v[202:203]
	v_pk_mul_f32 v[204:205], v[80:81], v[204:205]
	v_pk_mul_f32 v[206:207], v[70:71], v[206:207]
	v_pk_mul_f32 v[208:209], v[72:73], v[208:209]
	v_pk_mul_f32 v[194:195], v[194:195], v[90:91]
	v_pk_mul_f32 v[196:197], v[196:197], v[92:93]
	v_pk_mul_f32 v[198:199], v[198:199], v[82:83]
	v_pk_mul_f32 v[200:201], v[200:201], v[84:85]
	v_pk_mul_f32 v[202:203], v[202:203], v[74:75]
	v_pk_mul_f32 v[204:205], v[204:205], v[76:77]
	v_pk_mul_f32 v[206:207], v[206:207], v[66:67]
	v_pk_mul_f32 v[208:209], v[208:209], v[68:69]
	v_cvt_pk_bf16_f32 v194, v194, v195
	v_cvt_pk_bf16_f32 v195, v196, v197
	v_cvt_pk_bf16_f32 v196, v198, v199
	v_cvt_pk_bf16_f32 v197, v200, v201
	v_cvt_pk_bf16_f32 v202, v202, v203
	v_cvt_pk_bf16_f32 v203, v204, v205
	v_cvt_pk_bf16_f32 v204, v206, v207
	v_cvt_pk_bf16_f32 v205, v208, v209
	v_add_u32_e32 v141, 0x2c000, v140
	global_store_dwordx4 v141, v[194:197], s[0:1]
	v_add_u32_e32 v147, 0x42000, v140
	global_store_dwordx4 v147, v[202:205], s[0:1]
	v_pk_mul_f32 v[224:225], v[62:63], v[150:151]
	v_pk_mul_f32 v[226:227], v[64:65], v[150:151]
	v_pk_mul_f32 v[228:229], v[54:55], v[150:151]
	v_pk_mul_f32 v[230:231], v[56:57], v[150:151]
	v_pk_mul_f32 v[232:233], v[46:47], v[150:151]
	v_pk_mul_f32 v[234:235], v[48:49], v[150:151]
	v_pk_mul_f32 v[236:237], v[38:39], v[150:151]
	v_pk_mul_f32 v[238:239], v[40:41], v[150:151]
	v_exp_f32_e32 v224, v224
	v_exp_f32_e32 v225, v225
	v_exp_f32_e32 v226, v226
	v_exp_f32_e32 v227, v227
	v_exp_f32_e32 v228, v228
	v_exp_f32_e32 v229, v229
	v_exp_f32_e32 v230, v230
	v_exp_f32_e32 v231, v231
	v_exp_f32_e32 v232, v232
	v_exp_f32_e32 v233, v233
	v_exp_f32_e32 v234, v234
	v_exp_f32_e32 v235, v235
	v_exp_f32_e32 v236, v236
	v_exp_f32_e32 v237, v237
	v_exp_f32_e32 v238, v238
	v_exp_f32_e32 v239, v239
	v_pk_add_f32 v[224:225], v[224:225], v[152:153]
	v_pk_add_f32 v[226:227], v[226:227], v[152:153]
	v_pk_add_f32 v[228:229], v[228:229], v[152:153]
	v_pk_add_f32 v[230:231], v[230:231], v[152:153]
	v_pk_add_f32 v[232:233], v[232:233], v[152:153]
	v_pk_add_f32 v[234:235], v[234:235], v[152:153]
	v_pk_add_f32 v[236:237], v[236:237], v[152:153]
	v_pk_add_f32 v[238:239], v[238:239], v[152:153]
	v_rcp_f32_e32 v224, v224
	v_rcp_f32_e32 v225, v225
	v_rcp_f32_e32 v226, v226
	v_rcp_f32_e32 v227, v227
	v_rcp_f32_e32 v228, v228
	v_rcp_f32_e32 v229, v229
	v_rcp_f32_e32 v230, v230
	v_rcp_f32_e32 v231, v231
	v_rcp_f32_e32 v232, v232
	v_rcp_f32_e32 v233, v233
	v_rcp_f32_e32 v234, v234
	v_rcp_f32_e32 v235, v235
	v_rcp_f32_e32 v236, v236
	v_rcp_f32_e32 v237, v237
	v_rcp_f32_e32 v238, v238
	v_rcp_f32_e32 v239, v239
	v_pk_mul_f32 v[224:225], v[62:63], v[224:225]
	v_pk_mul_f32 v[226:227], v[64:65], v[226:227]
	v_pk_mul_f32 v[228:229], v[54:55], v[228:229]
	v_pk_mul_f32 v[230:231], v[56:57], v[230:231]
	v_pk_mul_f32 v[232:233], v[46:47], v[232:233]
	v_pk_mul_f32 v[234:235], v[48:49], v[234:235]
	v_pk_mul_f32 v[236:237], v[38:39], v[236:237]
	v_pk_mul_f32 v[238:239], v[40:41], v[238:239]
	v_pk_mul_f32 v[224:225], v[224:225], v[58:59]
	v_pk_mul_f32 v[226:227], v[226:227], v[60:61]
	v_pk_mul_f32 v[228:229], v[228:229], v[50:51]
	v_pk_mul_f32 v[230:231], v[230:231], v[52:53]
	v_pk_mul_f32 v[232:233], v[232:233], v[42:43]
	v_pk_mul_f32 v[234:235], v[234:235], v[44:45]
	v_pk_mul_f32 v[236:237], v[236:237], v[34:35]
	v_pk_mul_f32 v[238:239], v[238:239], v[36:37]
	v_cvt_pk_bf16_f32 v224, v224, v225
	v_cvt_pk_bf16_f32 v225, v226, v227
	v_cvt_pk_bf16_f32 v226, v228, v229
	v_cvt_pk_bf16_f32 v227, v230, v231
	v_cvt_pk_bf16_f32 v232, v232, v233
	v_cvt_pk_bf16_f32 v233, v234, v235
	v_cvt_pk_bf16_f32 v234, v236, v237
	v_cvt_pk_bf16_f32 v235, v238, v239
	v_add_u32_e32 v141, 0xb0000, v140
	global_store_dwordx4 v141, v[224:227], s[0:1]
	v_add_u32_e32 v147, 0xc6000, v140
	global_store_dwordx4 v147, v[232:235], s[0:1]
	v_pk_mul_f32 v[178:179], v[30:31], v[150:151]
	v_pk_mul_f32 v[180:181], v[32:33], v[150:151]
	v_pk_mul_f32 v[182:183], v[22:23], v[150:151]
	v_pk_mul_f32 v[184:185], v[24:25], v[150:151]
	v_pk_mul_f32 v[186:187], v[14:15], v[150:151]
	v_pk_mul_f32 v[188:189], v[16:17], v[150:151]
	v_pk_mul_f32 v[190:191], v[6:7], v[150:151]
	v_pk_mul_f32 v[192:193], v[8:9], v[150:151]
	v_exp_f32_e32 v178, v178
	v_exp_f32_e32 v179, v179
	v_exp_f32_e32 v180, v180
	v_exp_f32_e32 v181, v181
	v_exp_f32_e32 v182, v182
	v_exp_f32_e32 v183, v183
	v_exp_f32_e32 v184, v184
	v_exp_f32_e32 v185, v185
	v_exp_f32_e32 v186, v186
	v_exp_f32_e32 v187, v187
	v_exp_f32_e32 v188, v188
	v_exp_f32_e32 v189, v189
	v_exp_f32_e32 v190, v190
	v_exp_f32_e32 v191, v191
	v_exp_f32_e32 v192, v192
	v_exp_f32_e32 v193, v193
	v_pk_add_f32 v[178:179], v[178:179], v[152:153]
	v_pk_add_f32 v[180:181], v[180:181], v[152:153]
	v_pk_add_f32 v[182:183], v[182:183], v[152:153]
	v_pk_add_f32 v[184:185], v[184:185], v[152:153]
	v_pk_add_f32 v[186:187], v[186:187], v[152:153]
	v_pk_add_f32 v[188:189], v[188:189], v[152:153]
	v_pk_add_f32 v[190:191], v[190:191], v[152:153]
	v_pk_add_f32 v[192:193], v[192:193], v[152:153]
	v_rcp_f32_e32 v178, v178
	v_rcp_f32_e32 v179, v179
	v_rcp_f32_e32 v180, v180
	v_rcp_f32_e32 v181, v181
	v_rcp_f32_e32 v182, v182
	v_rcp_f32_e32 v183, v183
	v_rcp_f32_e32 v184, v184
	v_rcp_f32_e32 v185, v185
	v_rcp_f32_e32 v186, v186
	v_rcp_f32_e32 v187, v187
	v_rcp_f32_e32 v188, v188
	v_rcp_f32_e32 v189, v189
	v_rcp_f32_e32 v190, v190
	v_rcp_f32_e32 v191, v191
	v_rcp_f32_e32 v192, v192
	v_rcp_f32_e32 v193, v193
	v_pk_mul_f32 v[178:179], v[30:31], v[178:179]
	v_pk_mul_f32 v[180:181], v[32:33], v[180:181]
	v_pk_mul_f32 v[182:183], v[22:23], v[182:183]
	v_pk_mul_f32 v[184:185], v[24:25], v[184:185]
	v_pk_mul_f32 v[186:187], v[14:15], v[186:187]
	v_pk_mul_f32 v[188:189], v[16:17], v[188:189]
	v_pk_mul_f32 v[190:191], v[6:7], v[190:191]
	v_pk_mul_f32 v[192:193], v[8:9], v[192:193]
	v_pk_mul_f32 v[178:179], v[178:179], v[26:27]
	v_pk_mul_f32 v[180:181], v[180:181], v[28:29]
	v_pk_mul_f32 v[182:183], v[182:183], v[18:19]
	v_pk_mul_f32 v[184:185], v[184:185], v[20:21]
	v_pk_mul_f32 v[186:187], v[186:187], v[10:11]
	v_pk_mul_f32 v[188:189], v[188:189], v[12:13]
	v_pk_mul_f32 v[190:191], v[190:191], v[2:3]
	v_pk_mul_f32 v[192:193], v[192:193], v[4:5]
	v_cvt_pk_bf16_f32 v178, v178, v179
	v_cvt_pk_bf16_f32 v179, v180, v181
	v_cvt_pk_bf16_f32 v180, v182, v183
	v_cvt_pk_bf16_f32 v181, v184, v185
	v_cvt_pk_bf16_f32 v186, v186, v187
	v_cvt_pk_bf16_f32 v187, v188, v189
	v_cvt_pk_bf16_f32 v188, v190, v191
	v_cvt_pk_bf16_f32 v189, v192, v193
	v_add_u32_e32 v141, 0xdc000, v140
	global_store_dwordx4 v141, v[178:181], s[0:1]
	v_add_u32_e32 v147, 0xf2000, v140
	global_store_dwordx4 v147, v[186:189], s[0:1]
	s_nop 0
	s_and_b64 vcc, exec, s[4:5]
	s_mov_b64 s[0:1], -1
	s_cbranch_vccnz .LBB0_661
	s_andn2_b64 vcc, exec, s[12:13]
	s_cbranch_vccnz .LBB0_660
	s_barrier
	s_branch .LBB0_660
